# P0 layer-0 weight conversion done by the coalesced conversion routine on all CUs (replaces the scattered-store conversion code)
# speedup vs baseline: 1.0343x; 1.0027x over previous
.LBB0_14:
	s_or_b64 exec, exec, s[0:1]
	v_readlane_b32 s0, v252, 0
	s_ashr_i32 s34, s2, 6
	s_lshl_b32 s0, s0, 3
	s_add_i32 s12, s34, s0
	v_and_b32_e32 v1, 63, v34
	s_lshl_b32 s16, s3, 3
	s_mov_b32 s8, s7
	s_mov_b32 s13, s6
	s_mov_b32 s7, s34
	s_mov_b32 s62, -1
	s_mov_b32 s70, s12
	s_mov_b32 s71, s16
	s_movk_i32 s9, 0x2520
	s_branch .Ltail_go
.Lp0_ret:
	s_mov_b32 s7, s8
	s_mov_b32 s6, s13

.Ltail_end:
	s_cmp_eq_u32 s62, -1
	s_cbranch_scc1 .Lp0_ret
